# phase2 meta units: residual/rope tail loads batched (meta units now on the phase-2 critical workgroups)
# baseline (speedup 1.0000x reference)
.LBB0_449:
	s_or_b64 exec, exec, s[4:5]
	s_barrier
	s_and_saveexec_b64 s[8:9], s[2:3]
	s_cbranch_execz .LBB0_438
	v_mov_b32_e32 v41, 0
	s_mov_b64 s[4:5], 0
	v_add_co_u32_e32 v42, vcc, 0x19ff1000, v36
	v_mov_b32_e32 v43, v37
	s_nop 0
	v_addc_co_u32_e32 v43, vcc, 0, v43, vcc
	global_load_dwordx4 v[100:103], v[42:43], off offset:2048
	global_load_dwordx4 v[104:107], v[42:43], off offset:2064
	global_load_dwordx4 v[108:111], v[42:43], off offset:2080
	global_load_dwordx4 v[112:115], v[42:43], off offset:2096
	global_load_dwordx4 v[116:119], v[42:43], off offset:2112
	global_load_dwordx4 v[120:123], v[42:43], off offset:2128
	global_load_dwordx4 v[124:127], v[42:43], off offset:2144
	global_load_dwordx4 v[128:131], v[42:43], off offset:2160
	s_waitcnt vmcnt(0)
	v_lshlrev_b32_e32 v39, 16, v100
	v_and_b32_e32 v58, 0xffff0000, v100
	v_fmac_f32_e32 v41, v39, v39
	v_fmac_f32_e32 v41, v58, v58
	v_lshlrev_b32_e32 v39, 16, v101
	v_and_b32_e32 v58, 0xffff0000, v101
	v_fmac_f32_e32 v41, v39, v39
	v_fmac_f32_e32 v41, v58, v58
	v_lshlrev_b32_e32 v39, 16, v102
	v_and_b32_e32 v58, 0xffff0000, v102
	v_fmac_f32_e32 v41, v39, v39
	v_fmac_f32_e32 v41, v58, v58
	v_lshlrev_b32_e32 v39, 16, v103
	v_and_b32_e32 v58, 0xffff0000, v103
	v_fmac_f32_e32 v41, v39, v39
	v_fmac_f32_e32 v41, v58, v58
	v_lshlrev_b32_e32 v39, 16, v104
	v_and_b32_e32 v58, 0xffff0000, v104
	v_fmac_f32_e32 v41, v39, v39
	v_fmac_f32_e32 v41, v58, v58
	v_lshlrev_b32_e32 v39, 16, v105
	v_and_b32_e32 v58, 0xffff0000, v105
	v_fmac_f32_e32 v41, v39, v39
	v_fmac_f32_e32 v41, v58, v58
	v_lshlrev_b32_e32 v39, 16, v106
	v_and_b32_e32 v58, 0xffff0000, v106
	v_fmac_f32_e32 v41, v39, v39
	v_fmac_f32_e32 v41, v58, v58
	v_lshlrev_b32_e32 v39, 16, v107
	v_and_b32_e32 v58, 0xffff0000, v107
	v_fmac_f32_e32 v41, v39, v39
	v_fmac_f32_e32 v41, v58, v58
	v_lshlrev_b32_e32 v39, 16, v108
	v_and_b32_e32 v58, 0xffff0000, v108
	v_fmac_f32_e32 v41, v39, v39
	v_fmac_f32_e32 v41, v58, v58
	v_lshlrev_b32_e32 v39, 16, v109
	v_and_b32_e32 v58, 0xffff0000, v109
	v_fmac_f32_e32 v41, v39, v39
	v_fmac_f32_e32 v41, v58, v58
	v_lshlrev_b32_e32 v39, 16, v110
	v_and_b32_e32 v58, 0xffff0000, v110
	v_fmac_f32_e32 v41, v39, v39
	v_fmac_f32_e32 v41, v58, v58
	v_lshlrev_b32_e32 v39, 16, v111
	v_and_b32_e32 v58, 0xffff0000, v111
	v_fmac_f32_e32 v41, v39, v39
	v_fmac_f32_e32 v41, v58, v58
	v_lshlrev_b32_e32 v39, 16, v112
	v_and_b32_e32 v58, 0xffff0000, v112
	v_fmac_f32_e32 v41, v39, v39
	v_fmac_f32_e32 v41, v58, v58
	v_lshlrev_b32_e32 v39, 16, v113
	v_and_b32_e32 v58, 0xffff0000, v113
	v_fmac_f32_e32 v41, v39, v39
	v_fmac_f32_e32 v41, v58, v58
	v_lshlrev_b32_e32 v39, 16, v114
	v_and_b32_e32 v58, 0xffff0000, v114
	v_fmac_f32_e32 v41, v39, v39
	v_fmac_f32_e32 v41, v58, v58
	v_lshlrev_b32_e32 v39, 16, v115
	v_and_b32_e32 v58, 0xffff0000, v115
	v_fmac_f32_e32 v41, v39, v39
	v_fmac_f32_e32 v41, v58, v58
	v_lshlrev_b32_e32 v39, 16, v116
	v_and_b32_e32 v58, 0xffff0000, v116
	v_fmac_f32_e32 v41, v39, v39
	v_fmac_f32_e32 v41, v58, v58
	v_lshlrev_b32_e32 v39, 16, v117
	v_and_b32_e32 v58, 0xffff0000, v117
	v_fmac_f32_e32 v41, v39, v39
	v_fmac_f32_e32 v41, v58, v58
	v_lshlrev_b32_e32 v39, 16, v118
	v_and_b32_e32 v58, 0xffff0000, v118
	v_fmac_f32_e32 v41, v39, v39
	v_fmac_f32_e32 v41, v58, v58
	v_lshlrev_b32_e32 v39, 16, v119
	v_and_b32_e32 v58, 0xffff0000, v119
	v_fmac_f32_e32 v41, v39, v39
	v_fmac_f32_e32 v41, v58, v58
	v_lshlrev_b32_e32 v39, 16, v120
	v_and_b32_e32 v58, 0xffff0000, v120
	v_fmac_f32_e32 v41, v39, v39
	v_fmac_f32_e32 v41, v58, v58
	v_lshlrev_b32_e32 v39, 16, v121
	v_and_b32_e32 v58, 0xffff0000, v121
	v_fmac_f32_e32 v41, v39, v39
	v_fmac_f32_e32 v41, v58, v58
	v_lshlrev_b32_e32 v39, 16, v122
	v_and_b32_e32 v58, 0xffff0000, v122
	v_fmac_f32_e32 v41, v39, v39
	v_fmac_f32_e32 v41, v58, v58
	v_lshlrev_b32_e32 v39, 16, v123
	v_and_b32_e32 v58, 0xffff0000, v123
	v_fmac_f32_e32 v41, v39, v39
	v_fmac_f32_e32 v41, v58, v58
	v_lshlrev_b32_e32 v39, 16, v124
	v_and_b32_e32 v58, 0xffff0000, v124
	v_fmac_f32_e32 v41, v39, v39
	v_fmac_f32_e32 v41, v58, v58
	v_lshlrev_b32_e32 v39, 16, v125
	v_and_b32_e32 v58, 0xffff0000, v125
	v_fmac_f32_e32 v41, v39, v39
	v_fmac_f32_e32 v41, v58, v58
	v_lshlrev_b32_e32 v39, 16, v126
	v_and_b32_e32 v58, 0xffff0000, v126
	v_fmac_f32_e32 v41, v39, v39
	v_fmac_f32_e32 v41, v58, v58
	v_lshlrev_b32_e32 v39, 16, v127
	v_and_b32_e32 v58, 0xffff0000, v127
	v_fmac_f32_e32 v41, v39, v39
	v_fmac_f32_e32 v41, v58, v58
	v_lshlrev_b32_e32 v39, 16, v128
	v_and_b32_e32 v58, 0xffff0000, v128
	v_fmac_f32_e32 v41, v39, v39
	v_fmac_f32_e32 v41, v58, v58
	v_lshlrev_b32_e32 v39, 16, v129
	v_and_b32_e32 v58, 0xffff0000, v129
	v_fmac_f32_e32 v41, v39, v39
	v_fmac_f32_e32 v41, v58, v58
	v_lshlrev_b32_e32 v39, 16, v130
	v_and_b32_e32 v58, 0xffff0000, v130
	v_fmac_f32_e32 v41, v39, v39
	v_fmac_f32_e32 v41, v58, v58
	v_lshlrev_b32_e32 v39, 16, v131
	v_and_b32_e32 v58, 0xffff0000, v131
	v_fmac_f32_e32 v41, v39, v39
	v_fmac_f32_e32 v41, v58, v58
	v_and_b32_e32 v39, 64, v57
	v_xor_b32_e32 v42, 16, v57
	v_add_u32_e32 v43, 64, v39
	v_cmp_lt_i32_e32 vcc, v42, v43
	v_xor_b32_e32 v58, 32, v57
	s_mul_hi_i32 s0, s25, 0x55555556
	v_cndmask_b32_e32 v42, v57, v42, vcc
	v_lshlrev_b32_e32 v42, 2, v42
	ds_bpermute_b32 v42, v42, v41
	v_cmp_lt_i32_e32 vcc, v58, v43
	s_lshr_b32 s4, s0, 31
	s_add_i32 s0, s0, s4
	s_mul_i32 s0, s0, 3
	s_waitcnt lgkmcnt(0)
	v_add_f32_e32 v41, v41, v42
	v_cndmask_b32_e32 v42, v57, v58, vcc
	v_lshlrev_b32_e32 v42, 2, v42
	ds_bpermute_b32 v42, v42, v41
	s_sub_i32 s0, s25, s0
	s_cmp_eq_u32 s0, 2
	v_mov_b32_e32 v58, v6
	v_mov_b32_e32 v59, v2
	s_waitcnt lgkmcnt(0)
	v_add_f32_e32 v41, v41, v42
	v_fmamk_f32 v41, v41, 0x3b800000, v55
	v_mul_f32_e32 v42, 0x4b800000, v41
	v_cmp_gt_f32_e32 vcc, s15, v41
	s_cselect_b64 s[10:11], -1, 0
	s_cmp_lg_u32 s0, 2
	v_cndmask_b32_e32 v41, v41, v42, vcc
	v_rsq_f32_e32 v41, v41
	s_nop 0
	v_mul_f32_e32 v42, 0x45800000, v41
	v_cndmask_b32_e32 v41, v41, v42, vcc
	v_or_b32_e32 v42, v39, v45
	v_lshlrev_b32_e32 v42, 2, v42
	ds_bpermute_b32 v42, v42, v41
	s_waitcnt lgkmcnt(0)
	v_mul_f32_e32 v42, 0x3e16c740, v42
	v_pk_mul_f32 v[42:43], v[58:59], v[42:43] op_sel_hi:[1,0]
	s_cbranch_scc1 .LBB0_454
	global_load_dword v2, v[22:23], off
	global_load_dword v6, v[20:21], off
	s_waitcnt vmcnt(1)
	v_pk_mul_f32 v[58:59], v[42:43], v[2:3] op_sel:[1,0] op_sel_hi:[0,0]
	s_waitcnt vmcnt(0)
	v_pk_mul_f32 v[60:61], v[42:43], v[6:7] op_sel_hi:[1,0]
	v_pk_fma_f32 v[42:43], v[42:43], v[6:7], v[58:59] op_sel_hi:[1,0,1] neg_lo:[0,0,1] neg_hi:[0,0,1]
	s_nop 0
	v_add_f32_e32 v42, v60, v58
